# sb loop: the eight done-flag flat loads issued together with one wait
# speedup vs baseline: 1.0170x; 1.0170x over previous
; DI void sb_item(const Params& P, int b, int hd, int qt, char* lds) {
;     ...
;         if (lane == 0) flags[(it & 1) * 8 + w] = done ? 1 : 0;
;         asm volatile("s_waitcnt vmcnt(0)" ::: "memory");
;         __syncthreads();
;         int alld = 1;
; #pragma unroll
;         for (int i = 0; i < 8; ++i) alld &= flags[(it & 1) * 8 + i];
;         if (alld) break;
.LBB0_164:
	s_or_b64 exec, exec, s[8:9]
	s_mulk_i32 s17, 0xc020
	s_add_i32 s12, s30, s17
	s_add_i32 s13, s12, 0x8000
	s_mov_b64 s[8:9], src_shared_base
	v_mov_b32_e32 v34, s13
	v_mov_b32_e32 v35, s9
	s_add_i32 s8, s12, 0x8004
	s_waitcnt vmcnt(0)
	s_waitcnt vmcnt(0) lgkmcnt(0)
	s_barrier
	flat_load_dword v0, v[34:35] sc0 sc1
	s_add_i32 s8, s12, 0x8004
	v_mov_b32_e32 v220, s8
	v_mov_b32_e32 v221, s9
	flat_load_dword v236, v[220:221] sc0 sc1
	s_add_i32 s8, s12, 0x8008
	v_mov_b32_e32 v222, s8
	v_mov_b32_e32 v223, s9
	flat_load_dword v237, v[222:223] sc0 sc1
	s_add_i32 s8, s12, 0x800c
	v_mov_b32_e32 v224, s8
	v_mov_b32_e32 v225, s9
	flat_load_dword v238, v[224:225] sc0 sc1
	s_add_i32 s8, s12, 0x8010
	v_mov_b32_e32 v226, s8
	v_mov_b32_e32 v227, s9
	flat_load_dword v239, v[226:227] sc0 sc1
	s_add_i32 s8, s12, 0x8014
	v_mov_b32_e32 v228, s8
	v_mov_b32_e32 v229, s9
	flat_load_dword v240, v[228:229] sc0 sc1
	s_add_i32 s8, s12, 0x8018
	v_mov_b32_e32 v230, s8
	v_mov_b32_e32 v231, s9
	flat_load_dword v241, v[230:231] sc0 sc1
	s_add_i32 s8, s12, 0x801c
	v_mov_b32_e32 v232, s8
	v_mov_b32_e32 v233, s9
	flat_load_dword v242, v[232:233] sc0 sc1
	s_mov_b64 s[12:13], -1
	s_waitcnt vmcnt(0) lgkmcnt(0)
	v_bitop3_b32 v0, v0, v236, v237 bitop3:0x80
	v_bitop3_b32 v0, v0, v238, v239 bitop3:0x80
	v_bitop3_b32 v0, v0, v240, v241 bitop3:0x80
	v_bitop3_b32 v0, v0, 1, v242 bitop3:0x80
	v_cmp_eq_u32_e64 s[8:9], 0, v0
	s_and_saveexec_b64 s[14:15], s[8:9]
	s_cbranch_execz .LBB0_147
	s_add_i32 s29, s29, 1
	s_sub_i32 s16, s16, 64
	s_add_i32 s82, s82, -1
	s_addk_i32 s28, 0x4000
	s_cmpk_eq_i32 s16, 0xff80
	s_cselect_b64 s[8:9], -1, 0
	s_orn2_b64 s[12:13], s[8:9], exec
	s_branch .LBB0_147
